# v46 + m2 state scan: next-batch loads prefetched into spare registers (both the 131072-thread scan and the 2048-thread normaliser scan), in-batch store-draining waits dropped
# baseline (speedup 1.0000x reference)
.LBB0_491:
	v_and_b32_e32 v1, 0x1fff, v49
	v_ashrrev_i32_e32 v2, 7, v49
	v_and_b32_e32 v0, 0xffffffc0, v2
	v_cmp_eq_u32_e64 s[6:7], 0, v1
	v_lshlrev_b32_e32 v1, 1, v2
	v_and_b32_e32 v2, 0xffffff80, v1
	v_ashrrev_i32_e32 v1, 31, v0
	v_and_b32_e32 v4, 0x1fff, v48
	v_ashrrev_i32_e32 v3, 31, v2
	v_lshlrev_b64 v[20:21], 16, v[0:1]
	v_mov_b32_e32 v38, 0
	v_lshlrev_b64 v[16:17], 2, v[2:3]
	v_lshlrev_b64 v[18:19], 2, v[0:1]
	v_lshl_or_b32 v20, v4, 3, v20
	v_mov_b32_e32 v50, 0xff800000
	s_mov_b32 s22, -8
	v_mov_b32_e32 v39, v38
	v_mov_b32_e32 v40, v38
	v_mov_b32_e32 v41, v38
	s_waitcnt lgkmcnt(0)
	v_lshl_add_u64 v[92:93], s[4:5], 0, v[16:17]
	v_lshl_add_u64 v[94:95], s[4:5], 0, v[20:21]
	v_lshl_add_u64 v[92:93], v[92:93], 0, s[12:13]
	v_add_co_u32_e32 v94, vcc, 0xd800000, v94
	s_nop 1
	v_addc_co_u32_e32 v95, vcc, 0, v95, vcc
	global_load_dwordx4 v[60:63], v[92:93], off offset:48
	global_load_dwordx4 v[64:67], v[92:93], off offset:32
	global_load_dwordx4 v[68:71], v[92:93], off offset:16
	global_load_dwordx4 v[72:75], v[92:93], off
	global_load_dwordx2 v[76:77], v[94:95], off nt
	v_add_co_u32_e32 v94, vcc, 0x10000, v94
	s_nop 1
	v_addc_co_u32_e32 v95, vcc, 0, v95, vcc
	global_load_dwordx2 v[78:79], v[94:95], off nt
	v_add_co_u32_e32 v94, vcc, 0x10000, v94
	s_nop 1
	v_addc_co_u32_e32 v95, vcc, 0, v95, vcc
	global_load_dwordx2 v[80:81], v[94:95], off nt
	v_add_co_u32_e32 v94, vcc, 0x10000, v94
	s_nop 1
	v_addc_co_u32_e32 v95, vcc, 0, v95, vcc
	global_load_dwordx2 v[82:83], v[94:95], off nt
	v_add_co_u32_e32 v94, vcc, 0x10000, v94
	s_nop 1
	v_addc_co_u32_e32 v95, vcc, 0, v95, vcc
	global_load_dwordx2 v[84:85], v[94:95], off nt
	v_add_co_u32_e32 v94, vcc, 0x10000, v94
	s_nop 1
	v_addc_co_u32_e32 v95, vcc, 0, v95, vcc
	global_load_dwordx2 v[86:87], v[94:95], off nt
	v_add_co_u32_e32 v94, vcc, 0x10000, v94
	s_nop 1
	v_addc_co_u32_e32 v95, vcc, 0, v95, vcc
	global_load_dwordx2 v[88:89], v[94:95], off nt
	v_add_co_u32_e32 v94, vcc, 0x10000, v94
	s_nop 1
	v_addc_co_u32_e32 v95, vcc, 0, v95, vcc
	global_load_dwordx2 v[90:91], v[94:95], off nt
	s_waitcnt vmcnt(0)
	s_branch .LBB0_493
.LBB0_492:
	s_or_b64 exec, exec, s[16:17]
	v_add_f32_e32 v2, v8, v2
	v_max_f32_e32 v6, v3, v3
	v_max_f32_e32 v50, v2, v6
	v_sub_f32_e32 v2, v2, v50
	v_mul_f32_e32 v6, 0x3fb8aa3b, v2
	v_sub_f32_e32 v2, v3, v50
	v_mul_f32_e32 v2, 0x3fb8aa3b, v2
	v_exp_f32_e32 v2, v2
	v_exp_f32_e32 v6, v6
	v_lshlrev_b32_e32 v8, 16, v24
	v_and_b32_e32 v9, 0xffff0000, v24
	v_pk_mul_f32 v[8:9], v[2:3], v[8:9] op_sel_hi:[0,1]
	v_pk_fma_f32 v[40:41], v[0:1], v[6:7], v[8:9] op_sel_hi:[1,0,1]
	v_lshlrev_b32_e32 v0, 16, v25
	v_and_b32_e32 v1, 0xffff0000, v25
	v_pk_mul_f32 v[0:1], v[2:3], v[0:1] op_sel_hi:[0,1]
	s_add_i32 s22, s22, 8
	v_pk_fma_f32 v[38:39], v[4:5], v[6:7], v[0:1] op_sel_hi:[1,0,1]
	v_lshl_add_u64 v[16:17], v[16:17], 0, 64
	v_lshl_add_u64 v[18:19], v[18:19], 0, 32
	s_cmp_gt_u32 s22, 55
	v_lshl_add_u64 v[20:21], v[20:21], 0, s[14:15]
	s_cbranch_scc1 .LBB0_490
.LBB0_493:
	s_waitcnt lgkmcnt(0)
	v_lshl_add_u64 v[22:23], s[4:5], 0, v[20:21]
	s_waitcnt vmcnt(8)
	v_mov_b64_e32 v[0:1], v[60:61]
	v_mov_b64_e32 v[2:3], v[62:63]
	v_mov_b64_e32 v[4:5], v[64:65]
	v_mov_b64_e32 v[6:7], v[66:67]
	v_mov_b64_e32 v[8:9], v[68:69]
	v_mov_b64_e32 v[10:11], v[70:71]
	v_mov_b64_e32 v[12:13], v[72:73]
	v_mov_b64_e32 v[14:15], v[74:75]
	v_mov_b64_e32 v[44:45], v[76:77]
	v_mov_b64_e32 v[42:43], v[78:79]
	v_mov_b64_e32 v[36:37], v[80:81]
	v_mov_b64_e32 v[34:35], v[82:83]
	v_mov_b64_e32 v[32:33], v[84:85]
	v_mov_b64_e32 v[30:31], v[86:87]
	v_mov_b64_e32 v[28:29], v[88:89]
	v_mov_b64_e32 v[24:25], v[90:91]
	s_cmp_lt_i32 s22, 48
	s_cbranch_scc0 .Lm2_nopf
	v_lshl_add_u64 v[92:93], v[16:17], 0, 64
	v_lshl_add_u64 v[94:95], v[20:21], 0, s[14:15]
	v_lshl_add_u64 v[92:93], s[4:5], 0, v[92:93]
	v_lshl_add_u64 v[94:95], s[4:5], 0, v[94:95]
	v_lshl_add_u64 v[92:93], v[92:93], 0, s[12:13]
	v_add_co_u32_e32 v94, vcc, 0xd800000, v94
	s_nop 1
	v_addc_co_u32_e32 v95, vcc, 0, v95, vcc
	global_load_dwordx4 v[60:63], v[92:93], off offset:48
	global_load_dwordx4 v[64:67], v[92:93], off offset:32
	global_load_dwordx4 v[68:71], v[92:93], off offset:16
	global_load_dwordx4 v[72:75], v[92:93], off
	global_load_dwordx2 v[76:77], v[94:95], off nt
	v_add_co_u32_e32 v94, vcc, 0x10000, v94
	s_nop 1
	v_addc_co_u32_e32 v95, vcc, 0, v95, vcc
	global_load_dwordx2 v[78:79], v[94:95], off nt
	v_add_co_u32_e32 v94, vcc, 0x10000, v94
	s_nop 1
	v_addc_co_u32_e32 v95, vcc, 0, v95, vcc
	global_load_dwordx2 v[80:81], v[94:95], off nt
	v_add_co_u32_e32 v94, vcc, 0x10000, v94
	s_nop 1
	v_addc_co_u32_e32 v95, vcc, 0, v95, vcc
	global_load_dwordx2 v[82:83], v[94:95], off nt
	v_add_co_u32_e32 v94, vcc, 0x10000, v94
	s_nop 1
	v_addc_co_u32_e32 v95, vcc, 0, v95, vcc
	global_load_dwordx2 v[84:85], v[94:95], off nt
	v_add_co_u32_e32 v94, vcc, 0x10000, v94
	s_nop 1
	v_addc_co_u32_e32 v95, vcc, 0, v95, vcc
	global_load_dwordx2 v[86:87], v[94:95], off nt
	v_add_co_u32_e32 v94, vcc, 0x10000, v94
	s_nop 1
	v_addc_co_u32_e32 v95, vcc, 0, v95, vcc
	global_load_dwordx2 v[88:89], v[94:95], off nt
	v_add_co_u32_e32 v94, vcc, 0x10000, v94
	s_nop 1
	v_addc_co_u32_e32 v95, vcc, 0, v95, vcc
	global_load_dwordx2 v[90:91], v[94:95], off nt
.Lm2_nopf:
	v_add_co_u32_e32 v52, vcc, 0x9800000, v22
	v_cvt_pk_bf16_f32 v26, v40, v41
	v_cvt_pk_bf16_f32 v27, v38, v39
	v_addc_co_u32_e32 v53, vcc, 0, v23, vcc
	global_store_dwordx2 v[52:53], v[26:27], off
	v_lshl_add_u64 v[26:27], s[4:5], 0, v[18:19]
	s_and_saveexec_b64 s[16:17], s[6:7]
	s_cbranch_execz .LBB0_495
	v_add_co_u32_e32 v52, vcc, 0x1da40000, v26
	s_nop 1
	v_addc_co_u32_e32 v53, vcc, 0, v27, vcc
	global_store_dword v[52:53], v50, off
.LBB0_495:
	s_or_b64 exec, exec, s[16:17]
	v_add_f32_e32 v12, v50, v12
	v_max_f32_e32 v50, v13, v13
	v_max_f32_e32 v50, v12, v50
	v_sub_f32_e32 v13, v13, v50
	v_sub_f32_e32 v12, v12, v50
	v_mul_f32_e32 v13, 0x3fb8aa3b, v13
	v_mul_f32_e32 v12, 0x3fb8aa3b, v12
	v_exp_f32_e32 v52, v13
	v_exp_f32_e32 v54, v12
	v_lshlrev_b32_e32 v12, 16, v44
	v_and_b32_e32 v13, 0xffff0000, v44
	v_pk_mul_f32 v[12:13], v[52:53], v[12:13] op_sel_hi:[0,1]
	v_pk_fma_f32 v[12:13], v[40:41], v[54:55], v[12:13] op_sel_hi:[1,0,1]
	v_lshlrev_b32_e32 v40, 16, v45
	v_and_b32_e32 v41, 0xffff0000, v45
	v_pk_mul_f32 v[40:41], v[52:53], v[40:41] op_sel_hi:[0,1]
	v_pk_fma_f32 v[38:39], v[38:39], v[54:55], v[40:41] op_sel_hi:[1,0,1]
	v_add_co_u32_e32 v44, vcc, 0x9810000, v22
	v_cvt_pk_bf16_f32 v40, v12, v13
	v_cvt_pk_bf16_f32 v41, v38, v39
	v_addc_co_u32_e32 v45, vcc, 0, v23, vcc
	global_store_dwordx2 v[44:45], v[40:41], off
	s_and_saveexec_b64 s[16:17], s[6:7]
	s_cbranch_execz .LBB0_497
	v_add_co_u32_e32 v40, vcc, 0x1da40000, v26
	s_nop 1
	v_addc_co_u32_e32 v41, vcc, 0, v27, vcc
	global_store_dword v[40:41], v50, off offset:4
.LBB0_497:
	s_or_b64 exec, exec, s[16:17]
	v_add_f32_e32 v14, v50, v14
	v_max_f32_e32 v40, v15, v15
	v_max_f32_e32 v40, v14, v40
	v_sub_f32_e32 v14, v14, v40
	v_mul_f32_e32 v41, 0x3fb8aa3b, v14
	v_sub_f32_e32 v14, v15, v40
	v_mul_f32_e32 v14, 0x3fb8aa3b, v14
	v_exp_f32_e32 v14, v14
	v_exp_f32_e32 v44, v41
	v_lshlrev_b32_e32 v50, 16, v42
	v_and_b32_e32 v51, 0xffff0000, v42
	v_lshlrev_b32_e32 v42, 16, v43
	v_and_b32_e32 v43, 0xffff0000, v43
	v_pk_mul_f32 v[50:51], v[14:15], v[50:51] op_sel_hi:[0,1]
	v_pk_mul_f32 v[14:15], v[14:15], v[42:43] op_sel_hi:[0,1]
	v_pk_fma_f32 v[12:13], v[12:13], v[44:45], v[50:51] op_sel_hi:[1,0,1]
	v_pk_fma_f32 v[14:15], v[38:39], v[44:45], v[14:15] op_sel_hi:[1,0,1]
	v_add_co_u32_e32 v42, vcc, 0x9820000, v22
	v_cvt_pk_bf16_f32 v38, v12, v13
	v_cvt_pk_bf16_f32 v39, v14, v15
	v_addc_co_u32_e32 v43, vcc, 0, v23, vcc
	global_store_dwordx2 v[42:43], v[38:39], off
	s_and_saveexec_b64 s[16:17], s[6:7]
	s_cbranch_execz .LBB0_499
	v_add_co_u32_e32 v38, vcc, 0x1da40000, v26
	s_nop 1
	v_addc_co_u32_e32 v39, vcc, 0, v27, vcc
	global_store_dword v[38:39], v40, off offset:8
.LBB0_499:
	s_or_b64 exec, exec, s[16:17]
	v_add_f32_e32 v8, v40, v8
	v_max_f32_e32 v38, v9, v9
	v_max_f32_e32 v38, v8, v38
	v_sub_f32_e32 v9, v9, v38
	v_sub_f32_e32 v8, v8, v38
	v_mul_f32_e32 v9, 0x3fb8aa3b, v9
	v_mul_f32_e32 v8, 0x3fb8aa3b, v8
	v_exp_f32_e32 v40, v9
	v_exp_f32_e32 v42, v8
	v_lshlrev_b32_e32 v8, 16, v36
	v_and_b32_e32 v9, 0xffff0000, v36
	v_pk_mul_f32 v[8:9], v[40:41], v[8:9] op_sel_hi:[0,1]
	v_pk_fma_f32 v[8:9], v[12:13], v[42:43], v[8:9] op_sel_hi:[1,0,1]
	v_lshlrev_b32_e32 v12, 16, v37
	v_and_b32_e32 v13, 0xffff0000, v37
	v_pk_mul_f32 v[12:13], v[40:41], v[12:13] op_sel_hi:[0,1]
	v_pk_fma_f32 v[12:13], v[14:15], v[42:43], v[12:13] op_sel_hi:[1,0,1]
	v_add_co_u32_e32 v36, vcc, 0x9830000, v22
	v_cvt_pk_bf16_f32 v14, v8, v9
	v_cvt_pk_bf16_f32 v15, v12, v13
	v_addc_co_u32_e32 v37, vcc, 0, v23, vcc
	global_store_dwordx2 v[36:37], v[14:15], off
	s_and_saveexec_b64 s[16:17], s[6:7]
	s_cbranch_execz .LBB0_501
	v_add_co_u32_e32 v14, vcc, 0x1da40000, v26
	s_nop 1
	v_addc_co_u32_e32 v15, vcc, 0, v27, vcc
	global_store_dword v[14:15], v38, off offset:12
.LBB0_501:
	s_or_b64 exec, exec, s[16:17]
	v_add_f32_e32 v10, v38, v10
	v_max_f32_e32 v14, v11, v11
	v_max_f32_e32 v14, v10, v14
	v_sub_f32_e32 v10, v10, v14
	v_mul_f32_e32 v15, 0x3fb8aa3b, v10
	v_sub_f32_e32 v10, v11, v14
	v_mul_f32_e32 v10, 0x3fb8aa3b, v10
	v_exp_f32_e32 v10, v10
	v_exp_f32_e32 v36, v15
	v_lshlrev_b32_e32 v38, 16, v34
	v_and_b32_e32 v39, 0xffff0000, v34
	v_lshlrev_b32_e32 v34, 16, v35
	v_and_b32_e32 v35, 0xffff0000, v35
	v_pk_mul_f32 v[38:39], v[10:11], v[38:39] op_sel_hi:[0,1]
	v_pk_mul_f32 v[10:11], v[10:11], v[34:35] op_sel_hi:[0,1]
	v_pk_fma_f32 v[8:9], v[8:9], v[36:37], v[38:39] op_sel_hi:[1,0,1]
	v_pk_fma_f32 v[10:11], v[12:13], v[36:37], v[10:11] op_sel_hi:[1,0,1]
	v_add_co_u32_e32 v34, vcc, 0x9840000, v22
	v_cvt_pk_bf16_f32 v12, v8, v9
	v_cvt_pk_bf16_f32 v13, v10, v11
	v_addc_co_u32_e32 v35, vcc, 0, v23, vcc
	global_store_dwordx2 v[34:35], v[12:13], off
	s_and_saveexec_b64 s[16:17], s[6:7]
	s_cbranch_execz .LBB0_503
	v_add_co_u32_e32 v12, vcc, 0x1da40000, v26
	s_nop 1
	v_addc_co_u32_e32 v13, vcc, 0, v27, vcc
	global_store_dword v[12:13], v14, off offset:16
.LBB0_503:
	s_or_b64 exec, exec, s[16:17]
	v_add_f32_e32 v4, v14, v4
	v_max_f32_e32 v12, v5, v5
	v_max_f32_e32 v12, v4, v12
	v_sub_f32_e32 v5, v5, v12
	v_sub_f32_e32 v4, v4, v12
	v_mul_f32_e32 v5, 0x3fb8aa3b, v5
	v_mul_f32_e32 v4, 0x3fb8aa3b, v4
	v_exp_f32_e32 v14, v5
	v_exp_f32_e32 v34, v4
	v_lshlrev_b32_e32 v4, 16, v32
	v_and_b32_e32 v5, 0xffff0000, v32
	v_pk_mul_f32 v[4:5], v[14:15], v[4:5] op_sel_hi:[0,1]
	v_pk_fma_f32 v[4:5], v[8:9], v[34:35], v[4:5] op_sel_hi:[1,0,1]
	v_lshlrev_b32_e32 v8, 16, v33
	v_and_b32_e32 v9, 0xffff0000, v33
	v_pk_mul_f32 v[8:9], v[14:15], v[8:9] op_sel_hi:[0,1]
	v_pk_fma_f32 v[8:9], v[10:11], v[34:35], v[8:9] op_sel_hi:[1,0,1]
	v_add_co_u32_e32 v14, vcc, 0x9850000, v22
	v_cvt_pk_bf16_f32 v10, v4, v5
	v_cvt_pk_bf16_f32 v11, v8, v9
	v_addc_co_u32_e32 v15, vcc, 0, v23, vcc
	global_store_dwordx2 v[14:15], v[10:11], off
	s_and_saveexec_b64 s[16:17], s[6:7]
	s_cbranch_execz .LBB0_505
	v_add_co_u32_e32 v10, vcc, 0x1da40000, v26
	s_nop 1
	v_addc_co_u32_e32 v11, vcc, 0, v27, vcc
	global_store_dword v[10:11], v12, off offset:20
.LBB0_505:
	s_or_b64 exec, exec, s[16:17]
	v_add_f32_e32 v6, v12, v6
	v_max_f32_e32 v10, v7, v7
	v_max_f32_e32 v10, v6, v10
	v_sub_f32_e32 v6, v6, v10
	v_mul_f32_e32 v11, 0x3fb8aa3b, v6
	v_sub_f32_e32 v6, v7, v10
	v_mul_f32_e32 v6, 0x3fb8aa3b, v6
	v_exp_f32_e32 v6, v6
	v_exp_f32_e32 v12, v11
	v_lshlrev_b32_e32 v14, 16, v30
	v_and_b32_e32 v15, 0xffff0000, v30
	v_pk_mul_f32 v[14:15], v[6:7], v[14:15] op_sel_hi:[0,1]
	v_pk_fma_f32 v[4:5], v[4:5], v[12:13], v[14:15] op_sel_hi:[1,0,1]
	v_lshlrev_b32_e32 v14, 16, v31
	v_and_b32_e32 v15, 0xffff0000, v31
	v_pk_mul_f32 v[6:7], v[6:7], v[14:15] op_sel_hi:[0,1]
	v_pk_fma_f32 v[6:7], v[8:9], v[12:13], v[6:7] op_sel_hi:[1,0,1]
	v_add_co_u32_e32 v12, vcc, 0x9860000, v22
	v_cvt_pk_bf16_f32 v8, v4, v5
	v_cvt_pk_bf16_f32 v9, v6, v7
	v_addc_co_u32_e32 v13, vcc, 0, v23, vcc
	global_store_dwordx2 v[12:13], v[8:9], off
	s_and_saveexec_b64 s[16:17], s[6:7]
	s_cbranch_execz .LBB0_507
	v_add_co_u32_e32 v8, vcc, 0x1da40000, v26
	s_nop 1
	v_addc_co_u32_e32 v9, vcc, 0, v27, vcc
	global_store_dword v[8:9], v10, off offset:24
.LBB0_507:
	s_or_b64 exec, exec, s[16:17]
	v_add_f32_e32 v0, v10, v0
	v_max_f32_e32 v8, v1, v1
	v_max_f32_e32 v8, v0, v8
	v_sub_f32_e32 v1, v1, v8
	v_sub_f32_e32 v0, v0, v8
	v_mul_f32_e32 v1, 0x3fb8aa3b, v1
	v_mul_f32_e32 v0, 0x3fb8aa3b, v0
	v_exp_f32_e32 v10, v1
	v_exp_f32_e32 v12, v0
	v_lshlrev_b32_e32 v0, 16, v28
	v_and_b32_e32 v1, 0xffff0000, v28
	v_pk_mul_f32 v[0:1], v[10:11], v[0:1] op_sel_hi:[0,1]
	v_pk_fma_f32 v[0:1], v[4:5], v[12:13], v[0:1] op_sel_hi:[1,0,1]
	v_lshlrev_b32_e32 v4, 16, v29
	v_and_b32_e32 v5, 0xffff0000, v29
	v_pk_mul_f32 v[4:5], v[10:11], v[4:5] op_sel_hi:[0,1]
	v_pk_fma_f32 v[4:5], v[6:7], v[12:13], v[4:5] op_sel_hi:[1,0,1]
	v_add_co_u32_e32 v10, vcc, 0x9870000, v22
	v_cvt_pk_bf16_f32 v6, v0, v1
	v_cvt_pk_bf16_f32 v7, v4, v5
	v_addc_co_u32_e32 v11, vcc, 0, v23, vcc
	global_store_dwordx2 v[10:11], v[6:7], off
	s_and_saveexec_b64 s[16:17], s[6:7]
	s_cbranch_execz .LBB0_492
	v_add_co_u32_e32 v6, vcc, 0x1da40000, v26
	s_nop 1
	v_addc_co_u32_e32 v7, vcc, 0, v27, vcc
	global_store_dword v[6:7], v8, off offset:28
	s_branch .LBB0_492

.LBB0_511:
	v_ashrrev_i32_e32 v1, 1, v47
	v_and_b32_e32 v4, 0xffffffc0, v1
	v_and_b32_e32 v2, 0xffffff80, v47
	v_ashrrev_i32_e32 v5, 31, v4
	v_ashrrev_i32_e32 v3, 31, v2
	v_lshlrev_b64 v[4:5], 9, v[4:5]
	v_lshlrev_b64 v[2:3], 2, v[2:3]
	v_or_b32_e32 v4, v0, v4
	v_mov_b32_e32 v6, 0xff800000
	s_mov_b32 s16, 64
	v_mov_b32_e32 v1, 0
	s_waitcnt lgkmcnt(0)
	v_lshl_add_u64 v[92:93], s[4:5], 0, v[2:3]
	v_lshl_add_u64 v[94:95], s[4:5], 0, v[4:5]
	v_lshl_add_u64 v[92:93], v[92:93], 0, s[10:11]
	v_add_co_u32_e32 v94, vcc, s14, v94
	s_nop 1
	v_addc_co_u32_e32 v95, vcc, 0, v95, vcc
	global_load_dwordx4 v[60:63], v[92:93], off
	global_load_dwordx4 v[64:67], v[92:93], off offset:16
	global_load_dword v68, v[94:95], off
	global_load_dword v69, v[94:95], off offset:512
	global_load_dword v70, v[94:95], off offset:1024
	global_load_dword v71, v[94:95], off offset:1536
	s_waitcnt vmcnt(0)
.LBB0_512:
	s_waitcnt lgkmcnt(0)
	v_lshl_add_u64 v[16:17], s[4:5], 0, v[4:5]
	v_add_co_u32_e32 v18, vcc, 0x1d980000, v16
	s_nop 1
	v_addc_co_u32_e32 v19, vcc, 0, v17, vcc
	s_waitcnt vmcnt(4)
	v_mov_b64_e32 v[8:9], v[60:61]
	v_mov_b64_e32 v[10:11], v[62:63]
	v_mov_b64_e32 v[12:13], v[64:65]
	v_mov_b64_e32 v[14:15], v[66:67]
	v_mov_b32_e32 v7, v68
	v_mov_b32_e32 v20, v69
	v_mov_b32_e32 v21, v70
	v_mov_b32_e32 v16, v71
	v_lshl_add_u64 v[2:3], v[2:3], 0, 32
	v_lshl_add_u64 v[4:5], v[4:5], 0, s[12:13]
	s_cmp_lg_u32 s16, 4
	s_cbranch_scc0 .Lm2e_nopf
	v_lshl_add_u64 v[92:93], s[4:5], 0, v[2:3]
	v_lshl_add_u64 v[94:95], s[4:5], 0, v[4:5]
	v_lshl_add_u64 v[92:93], v[92:93], 0, s[10:11]
	v_add_co_u32_e32 v94, vcc, s14, v94
	s_nop 1
	v_addc_co_u32_e32 v95, vcc, 0, v95, vcc
	global_load_dwordx4 v[60:63], v[92:93], off
	global_load_dwordx4 v[64:67], v[92:93], off offset:16
	global_load_dword v68, v[94:95], off
	global_load_dword v69, v[94:95], off offset:512
	global_load_dword v70, v[94:95], off offset:1024
	global_load_dword v71, v[94:95], off offset:1536
.Lm2e_nopf:
	global_store_dword v[18:19], v1, off
	s_add_i32 s16, s16, -4
	s_cmp_eq_u32 s16, 0
	v_add_f32_e32 v6, v6, v8
	v_max_f32_e32 v8, v9, v9
	v_max_f32_e32 v8, v6, v8
	v_max_f32_e32 v17, v11, v11
	v_sub_f32_e32 v6, v6, v8
	v_sub_f32_e32 v9, v9, v8
	v_add_f32_e32 v8, v8, v10
	v_mul_f32_e32 v6, 0x3fb8aa3b, v6
	v_mul_f32_e32 v9, 0x3fb8aa3b, v9
	v_max_f32_e32 v10, v8, v17
	v_max_f32_e32 v22, v13, v13
	v_exp_f32_e32 v17, v6
	v_exp_f32_e32 v9, v9
	v_sub_f32_e32 v6, v8, v10
	v_sub_f32_e32 v8, v11, v10
	v_add_f32_e32 v10, v10, v12
	v_mul_f32_e32 v6, 0x3fb8aa3b, v6
	v_max_f32_e32 v11, v10, v22
	v_max_f32_e32 v23, v15, v15
	v_exp_f32_e32 v12, v6
	v_sub_f32_e32 v6, v10, v11
	v_sub_f32_e32 v10, v13, v11
	v_add_f32_e32 v11, v11, v14
	v_mul_f32_e32 v8, 0x3fb8aa3b, v8
	v_mul_f32_e32 v13, 0x3fb8aa3b, v6
	v_max_f32_e32 v6, v11, v23
	v_exp_f32_e32 v8, v8
	v_mul_f32_e32 v10, 0x3fb8aa3b, v10
	v_mul_f32_e32 v7, v7, v9
	v_exp_f32_e32 v9, v13
	v_sub_f32_e32 v11, v11, v6
	v_sub_f32_e32 v13, v15, v6
	v_exp_f32_e32 v10, v10
	v_fmac_f32_e32 v7, v1, v17
	v_mul_f32_e32 v1, 0x3fb8aa3b, v11
	v_mul_f32_e32 v11, 0x3fb8aa3b, v13
	v_exp_f32_e32 v13, v1
	v_exp_f32_e32 v1, v11
	v_mul_f32_e32 v8, v20, v8
	global_store_dword v[18:19], v7, off offset:512
	v_fmac_f32_e32 v8, v7, v12
	v_mul_f32_e32 v7, v21, v10
	v_fmac_f32_e32 v7, v8, v9
	v_mul_f32_e32 v1, v16, v1
	v_fmac_f32_e32 v1, v7, v13
	global_store_dword v[18:19], v8, off offset:1024
	global_store_dword v[18:19], v7, off offset:1536
	s_cbranch_scc0 .LBB0_512
	v_add_u32_e32 v47, s20, v47
	v_cmp_lt_i32_e32 vcc, s15, v47
	s_or_b64 s[8:9], vcc, s[8:9]
	s_andn2_b64 exec, exec, s[8:9]
	s_cbranch_execnz .LBB0_511
